# non-temporal hint on the residual-tile loads in the down/out-projection epilogues, on top of full-line GEMM staging
# baseline (speedup 1.0000x reference)
.LBB0_299:
	s_ashr_i32 s18, s44, 4
	s_load_dwordx16 s[56:71], s[0:1], 0x0
	v_lshl_or_b32 v144, s45, 8, v168
	s_mul_hi_i32 s19, s18, 0x9000
	s_mul_i32 s18, s18, 0x9000
	s_add_u32 s18, s34, s18
	v_ashrrev_i32_e32 v145, 31, v144
	s_addc_u32 s19, s35, s19
	v_lshlrev_b64 v[164:165], 2, v[144:145]
	v_lshl_add_u32 v162, s44, 8, v166
	v_lshl_add_u64 v[158:159], s[18:19], 0, v[164:165]
	v_ashrrev_i32_e32 v163, 31, v162
	global_load_dwordx4 v[146:149], v[158:159], off
	global_load_dwordx4 v[150:153], v[158:159], off offset:16
	global_load_dwordx4 v[154:157], v[158:159], off offset:512
	s_nop 0
	global_load_dwordx4 v[158:161], v[158:159], off offset:528
	v_lshlrev_b64 v[172:173], 12, v[162:163]
	s_waitcnt lgkmcnt(0)
	v_lshl_add_u64 v[164:165], s[56:57], 0, v[164:165]
	v_lshl_add_u64 v[184:185], v[164:165], 0, v[172:173]
	v_or_b32_e32 v220, 16, v162
	global_load_dwordx4 v[172:175], v[184:185], off nt
	global_load_dwordx4 v[176:179], v[184:185], off offset:16 nt
	global_load_dwordx4 v[180:183], v[184:185], off offset:528 nt
	s_nop 0
	global_load_dwordx4 v[184:187], v[184:185], off offset:512 nt
	v_ashrrev_i32_e32 v221, 31, v220
	v_lshlrev_b64 v[188:189], 12, v[220:221]
	v_lshl_add_u64 v[200:201], v[164:165], 0, v[188:189]
	v_or_b32_e32 v238, 32, v162
	global_load_dwordx4 v[188:191], v[200:201], off nt
	global_load_dwordx4 v[192:195], v[200:201], off offset:16 nt
	global_load_dwordx4 v[196:199], v[200:201], off offset:512 nt
	s_nop 0
	global_load_dwordx4 v[200:203], v[200:201], off offset:528 nt
	v_ashrrev_i32_e32 v239, 31, v238
	v_lshlrev_b64 v[204:205], 12, v[238:239]
	v_lshl_add_u64 v[216:217], v[164:165], 0, v[204:205]
	global_load_dwordx4 v[204:207], v[216:217], off nt
	global_load_dwordx4 v[208:211], v[216:217], off offset:16 nt
	v_or_b32_e32 v240, 48, v162
	global_load_dwordx4 v[212:215], v[216:217], off offset:528 nt
	s_nop 0
	global_load_dwordx4 v[216:219], v[216:217], off offset:512 nt
	v_ashrrev_i32_e32 v241, 31, v240
	v_lshlrev_b64 v[222:223], 11, v[162:163]
	v_lshlrev_b64 v[224:225], 12, v[240:241]
	v_lshlrev_b64 v[144:145], 1, v[144:145]
	v_lshl_add_u64 v[222:223], s[80:81], 0, v[222:223]
	v_lshl_add_u64 v[232:233], v[164:165], 0, v[224:225]
	v_lshlrev_b64 v[242:243], 11, v[220:221]
	v_lshl_add_u64 v[244:245], v[222:223], 0, v[144:145]
	global_load_dwordx4 v[220:223], v[232:233], off offset:16 nt
	global_load_dwordx4 v[224:227], v[232:233], off nt
	global_load_dwordx4 v[228:231], v[232:233], off offset:528 nt
	s_nop 0
	global_load_dwordx4 v[232:235], v[232:233], off offset:512 nt
	s_and_b64 vcc, exec, s[6:7]
	s_mov_b64 s[6:7], -1
	s_waitcnt vmcnt(0)
	v_pk_add_f32 v[148:149], v[148:149], 1.0 op_sel_hi:[1,0]
	v_pk_add_f32 v[146:147], v[146:147], 1.0 op_sel_hi:[1,0]
	v_pk_add_f32 v[152:153], v[152:153], 1.0 op_sel_hi:[1,0]
	v_pk_add_f32 v[248:249], v[154:155], 1.0 op_sel_hi:[1,0]
	v_pk_add_f32 v[252:253], v[158:159], 1.0 op_sel_hi:[1,0]
	v_pk_add_f32 v[150:151], v[150:151], 1.0 op_sel_hi:[1,0]
	v_pk_add_f32 v[246:247], v[156:157], 1.0 op_sel_hi:[1,0]
	v_pk_add_f32 v[250:251], v[160:161], 1.0 op_sel_hi:[1,0]
	v_pk_mul_f32 v[158:159], v[148:149], 0.5 op_sel_hi:[1,0]
	v_pk_mul_f32 v[160:161], v[146:147], 0.5 op_sel_hi:[1,0]
	v_pk_mul_f32 v[154:155], v[152:153], 0.5 op_sel_hi:[1,0]
	v_pk_mul_f32 v[152:153], v[248:249], 0.5 op_sel_hi:[1,0]
	v_pk_mul_f32 v[148:149], v[252:253], 0.5 op_sel_hi:[1,0]
	v_pk_mul_f32 v[156:157], v[150:151], 0.5 op_sel_hi:[1,0]
	v_pk_mul_f32 v[150:151], v[246:247], 0.5 op_sel_hi:[1,0]
	v_pk_mul_f32 v[146:147], v[250:251], 0.5 op_sel_hi:[1,0]
	v_pk_fma_f32 v[126:127], v[126:127], v[158:159], v[174:175]
	v_pk_fma_f32 v[124:125], v[124:125], v[160:161], v[172:173]
	v_pk_fma_f32 v[108:109], v[108:109], v[152:153], v[184:185]
	v_pk_fma_f32 v[174:175], v[104:105], v[148:149], v[180:181]
	v_cvt_pk_bf16_f32 v104, v124, v125
	v_cvt_pk_bf16_f32 v105, v126, v127
	v_pk_fma_f32 v[122:123], v[122:123], v[154:155], v[178:179]
	v_pk_fma_f32 v[120:121], v[120:121], v[156:157], v[176:177]
	v_pk_fma_f32 v[110:111], v[110:111], v[150:151], v[186:187]
	v_pk_fma_f32 v[172:173], v[106:107], v[146:147], v[182:183]
	v_cvt_pk_bf16_f32 v106, v120, v121
	v_cvt_pk_bf16_f32 v107, v122, v123
	global_store_dwordx4 v[244:245], v[104:107], off
	v_pk_fma_f32 v[118:119], v[118:119], v[158:159], v[190:191]
	v_pk_fma_f32 v[116:117], v[116:117], v[160:161], v[188:189]
	v_cvt_pk_bf16_f32 v104, v108, v109
	v_cvt_pk_bf16_f32 v105, v110, v111
	v_lshl_add_u64 v[108:109], s[80:81], 0, v[242:243]
	v_cvt_pk_bf16_f32 v106, v174, v175
	v_cvt_pk_bf16_f32 v107, v172, v173
	global_store_dwordx4 v[244:245], v[104:107], off offset:256
	v_lshl_add_u64 v[108:109], v[108:109], 0, v[144:145]
	v_pk_fma_f32 v[114:115], v[114:115], v[154:155], v[194:195]
	v_cvt_pk_bf16_f32 v104, v116, v117
	v_cvt_pk_bf16_f32 v105, v118, v119
	v_pk_fma_f32 v[112:113], v[112:113], v[156:157], v[192:193]
	v_pk_fma_f32 v[102:103], v[102:103], v[150:151], v[198:199]
	v_cvt_pk_bf16_f32 v106, v112, v113
	v_cvt_pk_bf16_f32 v107, v114, v115
	global_store_dwordx4 v[108:109], v[104:107], off
	v_pk_fma_f32 v[100:101], v[100:101], v[152:153], v[196:197]
	v_pk_fma_f32 v[96:97], v[96:97], v[160:161], v[204:205]
	v_pk_fma_f32 v[104:105], v[94:95], v[146:147], v[202:203]
	v_pk_fma_f32 v[94:95], v[92:93], v[148:149], v[200:201]
	v_cvt_pk_bf16_f32 v92, v100, v101
	v_cvt_pk_bf16_f32 v93, v102, v103
	v_pk_fma_f32 v[86:87], v[86:87], v[150:151], v[218:219]
	v_cvt_pk_bf16_f32 v94, v94, v95
	v_cvt_pk_bf16_f32 v95, v104, v105
	global_store_dwordx4 v[108:109], v[92:95], off offset:256
	v_pk_fma_f32 v[84:85], v[84:85], v[152:153], v[216:217]
	v_pk_fma_f32 v[80:81], v[80:81], v[160:161], v[224:225]
	v_lshlrev_b64 v[92:93], 11, v[238:239]
	v_lshl_add_u64 v[92:93], s[80:81], 0, v[92:93]
	v_pk_fma_f32 v[94:95], v[98:99], v[158:159], v[206:207]
	v_pk_fma_f32 v[98:99], v[90:91], v[154:155], v[210:211]
	v_pk_fma_f32 v[90:91], v[88:89], v[156:157], v[208:209]
	v_cvt_pk_bf16_f32 v88, v96, v97
	v_cvt_pk_bf16_f32 v89, v94, v95
	v_lshl_add_u64 v[92:93], v[92:93], 0, v[144:145]
	v_cvt_pk_bf16_f32 v90, v90, v91
	v_cvt_pk_bf16_f32 v91, v98, v99
	global_store_dwordx4 v[92:93], v[88:91], off
	v_add_u32_e32 v172, 0x80, v162
	v_pk_fma_f32 v[70:71], v[70:71], v[150:151], v[234:235]
	v_pk_fma_f32 v[88:89], v[78:79], v[146:147], v[214:215]
	v_pk_fma_f32 v[78:79], v[76:77], v[148:149], v[212:213]
	v_cvt_pk_bf16_f32 v76, v84, v85
	v_cvt_pk_bf16_f32 v77, v86, v87
	v_pk_fma_f32 v[68:69], v[68:69], v[152:153], v[232:233]
	v_cvt_pk_bf16_f32 v78, v78, v79
	v_cvt_pk_bf16_f32 v79, v88, v89
	global_store_dwordx4 v[92:93], v[76:79], off offset:256
	v_ashrrev_i32_e32 v173, 31, v172
	v_add_u32_e32 v174, 0x90, v162
	v_lshlrev_b64 v[76:77], 11, v[240:241]
	v_lshl_add_u64 v[76:77], s[80:81], 0, v[76:77]
	v_pk_fma_f32 v[78:79], v[82:83], v[158:159], v[226:227]
	v_pk_fma_f32 v[82:83], v[74:75], v[154:155], v[222:223]
	v_pk_fma_f32 v[74:75], v[72:73], v[156:157], v[220:221]
	v_cvt_pk_bf16_f32 v72, v80, v81
	v_cvt_pk_bf16_f32 v73, v78, v79
	v_lshl_add_u64 v[76:77], v[76:77], 0, v[144:145]
	v_cvt_pk_bf16_f32 v74, v74, v75
	v_cvt_pk_bf16_f32 v75, v82, v83
	global_store_dwordx4 v[76:77], v[72:75], off
	v_ashrrev_i32_e32 v175, 31, v174
	v_lshlrev_b64 v[80:81], 12, v[174:175]
	v_pk_fma_f32 v[72:73], v[66:67], v[146:147], v[230:231]
	v_pk_fma_f32 v[66:67], v[64:65], v[148:149], v[228:229]
	v_cvt_pk_bf16_f32 v64, v68, v69
	v_cvt_pk_bf16_f32 v65, v70, v71
	v_lshl_add_u64 v[92:93], v[164:165], 0, v[80:81]
	v_cvt_pk_bf16_f32 v66, v66, v67
	v_cvt_pk_bf16_f32 v67, v72, v73
	global_store_dwordx4 v[76:77], v[64:67], off offset:256
	v_add_u32_e32 v176, 0xa0, v162
	v_ashrrev_i32_e32 v177, 31, v176
	v_lshlrev_b64 v[64:65], 12, v[172:173]
	v_lshl_add_u64 v[76:77], v[164:165], 0, v[64:65]
	global_load_dwordx4 v[64:67], v[76:77], off nt
	global_load_dwordx4 v[68:71], v[76:77], off offset:16 nt
	global_load_dwordx4 v[72:75], v[76:77], off offset:512 nt
	s_nop 0
	global_load_dwordx4 v[76:79], v[76:77], off offset:528 nt
	s_nop 0
	global_load_dwordx4 v[80:83], v[92:93], off nt
	global_load_dwordx4 v[84:87], v[92:93], off offset:16 nt
	global_load_dwordx4 v[88:91], v[92:93], off offset:512 nt
	s_nop 0
	global_load_dwordx4 v[92:95], v[92:93], off offset:528 nt
	v_lshlrev_b64 v[96:97], 12, v[176:177]
	v_lshl_add_u64 v[108:109], v[164:165], 0, v[96:97]
	global_load_dwordx4 v[96:99], v[108:109], off nt
	global_load_dwordx4 v[100:103], v[108:109], off offset:16 nt
	global_load_dwordx4 v[104:107], v[108:109], off offset:512 nt
	s_nop 0
	global_load_dwordx4 v[108:111], v[108:109], off offset:528 nt
	v_add_u32_e32 v162, 0xb0, v162
	v_ashrrev_i32_e32 v163, 31, v162
	v_lshlrev_b64 v[112:113], 12, v[162:163]
	v_lshl_add_u64 v[124:125], v[164:165], 0, v[112:113]
	global_load_dwordx4 v[112:115], v[124:125], off nt
	global_load_dwordx4 v[116:119], v[124:125], off offset:16 nt
	global_load_dwordx4 v[120:123], v[124:125], off offset:512 nt
	s_nop 0
	global_load_dwordx4 v[124:127], v[124:125], off offset:528 nt
	v_lshlrev_b64 v[164:165], 11, v[172:173]
	s_waitcnt vmcnt(15)
	v_pk_fma_f32 v[60:61], v[60:61], v[160:161], v[64:65]
	s_waitcnt vmcnt(14)
	v_pk_fma_f32 v[64:65], v[58:59], v[154:155], v[70:71]
	v_pk_fma_f32 v[58:59], v[56:57], v[156:157], v[68:69]
	v_cvt_pk_bf16_f32 v56, v60, v61
	v_lshl_add_u64 v[60:61], s[80:81], 0, v[164:165]
	v_pk_fma_f32 v[62:63], v[62:63], v[158:159], v[66:67]
	v_lshl_add_u64 v[60:61], v[60:61], 0, v[144:145]
	v_cvt_pk_bf16_f32 v57, v62, v63
	v_cvt_pk_bf16_f32 v58, v58, v59
	v_cvt_pk_bf16_f32 v59, v64, v65
	global_store_dwordx4 v[60:61], v[56:59], off
	s_waitcnt vmcnt(14)
	v_pk_fma_f32 v[54:55], v[54:55], v[150:151], v[74:75]
	v_pk_fma_f32 v[52:53], v[52:53], v[152:153], v[72:73]
	s_waitcnt vmcnt(13)
	v_pk_fma_f32 v[56:57], v[46:47], v[146:147], v[78:79]
	v_pk_fma_f32 v[46:47], v[44:45], v[148:149], v[76:77]
	v_cvt_pk_bf16_f32 v44, v52, v53
	v_cvt_pk_bf16_f32 v45, v54, v55
	s_waitcnt vmcnt(12)
	v_pk_fma_f32 v[48:49], v[48:49], v[160:161], v[80:81]
	v_cvt_pk_bf16_f32 v46, v46, v47
	v_cvt_pk_bf16_f32 v47, v56, v57
	global_store_dwordx4 v[60:61], v[44:47], off offset:256
	s_waitcnt vmcnt(11)
	v_pk_fma_f32 v[38:39], v[38:39], v[150:151], v[90:91]
	v_pk_fma_f32 v[36:37], v[36:37], v[152:153], v[88:89]
	v_lshlrev_b64 v[44:45], 11, v[174:175]
	v_lshl_add_u64 v[44:45], s[80:81], 0, v[44:45]
	v_pk_fma_f32 v[46:47], v[50:51], v[158:159], v[82:83]
	v_pk_fma_f32 v[50:51], v[42:43], v[154:155], v[86:87]
	v_pk_fma_f32 v[42:43], v[40:41], v[156:157], v[84:85]
	v_cvt_pk_bf16_f32 v40, v48, v49
	v_cvt_pk_bf16_f32 v41, v46, v47
	v_lshl_add_u64 v[44:45], v[44:45], 0, v[144:145]
	v_cvt_pk_bf16_f32 v42, v42, v43
	v_cvt_pk_bf16_f32 v43, v50, v51
	global_store_dwordx4 v[44:45], v[40:43], off
	s_waitcnt vmcnt(10)
	v_pk_fma_f32 v[32:33], v[32:33], v[160:161], v[96:97]
	s_waitcnt vmcnt(8)
	v_pk_fma_f32 v[22:23], v[22:23], v[150:151], v[106:107]
	v_pk_fma_f32 v[40:41], v[30:31], v[146:147], v[94:95]
	v_pk_fma_f32 v[30:31], v[28:29], v[148:149], v[92:93]
	v_cvt_pk_bf16_f32 v28, v36, v37
	v_cvt_pk_bf16_f32 v29, v38, v39
	v_pk_fma_f32 v[20:21], v[20:21], v[152:153], v[104:105]
	v_cvt_pk_bf16_f32 v30, v30, v31
	v_cvt_pk_bf16_f32 v31, v40, v41
	global_store_dwordx4 v[44:45], v[28:31], off offset:256
	s_waitcnt vmcnt(7)
	v_pk_fma_f32 v[16:17], v[16:17], v[160:161], v[112:113]
	s_waitcnt vmcnt(5)
	v_pk_fma_f32 v[6:7], v[6:7], v[150:151], v[122:123]
	v_lshlrev_b64 v[28:29], 11, v[176:177]
	v_lshl_add_u64 v[28:29], s[80:81], 0, v[28:29]
	v_pk_fma_f32 v[30:31], v[34:35], v[158:159], v[98:99]
	v_pk_fma_f32 v[34:35], v[26:27], v[154:155], v[102:103]
	v_pk_fma_f32 v[26:27], v[24:25], v[156:157], v[100:101]
	v_cvt_pk_bf16_f32 v24, v32, v33
	v_cvt_pk_bf16_f32 v25, v30, v31
	v_lshl_add_u64 v[28:29], v[28:29], 0, v[144:145]
	v_cvt_pk_bf16_f32 v26, v26, v27
	v_cvt_pk_bf16_f32 v27, v34, v35
	global_store_dwordx4 v[28:29], v[24:27], off
	v_pk_fma_f32 v[4:5], v[4:5], v[152:153], v[120:121]
	s_nop 0
	v_pk_fma_f32 v[24:25], v[14:15], v[146:147], v[110:111]
	v_pk_fma_f32 v[14:15], v[12:13], v[148:149], v[108:109]
	v_cvt_pk_bf16_f32 v12, v20, v21
	v_cvt_pk_bf16_f32 v13, v22, v23
	s_nop 0
	v_cvt_pk_bf16_f32 v14, v14, v15
	v_cvt_pk_bf16_f32 v15, v24, v25
	global_store_dwordx4 v[28:29], v[12:15], off offset:256
	s_nop 1
	v_lshlrev_b64 v[12:13], 11, v[162:163]
	v_lshl_add_u64 v[12:13], s[80:81], 0, v[12:13]
	v_pk_fma_f32 v[14:15], v[18:19], v[158:159], v[114:115]
	v_pk_fma_f32 v[18:19], v[10:11], v[154:155], v[118:119]
	v_pk_fma_f32 v[10:11], v[8:9], v[156:157], v[116:117]
	v_cvt_pk_bf16_f32 v8, v16, v17
	v_cvt_pk_bf16_f32 v9, v14, v15
	v_lshl_add_u64 v[12:13], v[12:13], 0, v[144:145]
	v_cvt_pk_bf16_f32 v10, v10, v11
	v_cvt_pk_bf16_f32 v11, v18, v19
	global_store_dwordx4 v[12:13], v[8:11], off
	s_waitcnt vmcnt(7)
	s_nop 0
	v_pk_fma_f32 v[8:9], v[2:3], v[146:147], v[126:127]
	v_pk_fma_f32 v[2:3], v[0:1], v[148:149], v[124:125]
	v_cvt_pk_bf16_f32 v0, v4, v5
	v_cvt_pk_bf16_f32 v1, v6, v7
	s_nop 0
	v_cvt_pk_bf16_f32 v2, v2, v3
	v_cvt_pk_bf16_f32 v3, v8, v9
	global_store_dwordx4 v[12:13], v[0:3], off offset:256
	s_cbranch_vccnz .LBB0_284
	s_andn2_b64 vcc, exec, s[10:11]
	s_cbranch_vccnz .LBB0_283
	s_barrier
	s_branch .LBB0_283

.LBB0_1029:
	v_lshl_or_b32 v152, s30, 8, v186
	v_lshl_add_u32 v180, s28, 8, v184
	s_ashr_i32 s21, s28, 4
	v_ashrrev_i32_e32 v153, 31, v152
	v_ashrrev_i32_e32 v181, 31, v180
	s_mul_hi_i32 s23, s21, 0x9000
	s_mul_i32 s21, s21, 0x9000
	v_lshl_add_u64 v[178:179], v[152:153], 1, s[80:81]
	v_lshlrev_b64 v[128:129], 11, v[180:181]
	s_add_u32 s28, s44, s21
	v_lshl_add_u64 v[128:129], v[178:179], 0, v[128:129]
	s_addc_u32 s29, s45, s23
	v_lshlrev_b64 v[130:131], 2, v[152:153]
	global_load_dwordx4 v[154:157], v[128:129], off nt
	v_lshl_add_u64 v[132:133], s[28:29], 0, v[130:131]
	s_add_u32 s28, s46, s21
	s_addc_u32 s29, s47, s23
	global_load_dwordx4 v[158:161], v[132:133], off
	global_load_dwordx4 v[162:165], v[132:133], off offset:16
	global_load_dwordx4 v[166:169], v[132:133], off offset:512
	global_load_dwordx4 v[192:195], v[132:133], off offset:528
	v_lshl_add_u64 v[132:133], s[28:29], 0, v[130:131]
	global_load_dwordx4 v[196:199], v[132:133], off
	global_load_dwordx4 v[200:203], v[132:133], off offset:16
	global_load_dwordx4 v[204:207], v[132:133], off offset:512
	global_load_dwordx4 v[208:211], v[132:133], off offset:528
	v_lshl_add_u64 v[130:131], s[12:13], 0, v[130:131]
	global_load_dwordx4 v[212:215], v[130:131], off
	global_load_dwordx4 v[216:219], v[130:131], off offset:16
	global_load_dwordx4 v[220:223], v[130:131], off offset:512
	global_load_dwordx4 v[224:227], v[130:131], off offset:528
	global_load_dwordx4 v[228:231], v[128:129], off offset:256 nt
	v_or_b32_e32 v182, 16, v180
	v_ashrrev_i32_e32 v183, 31, v182
	v_lshlrev_b64 v[128:129], 10, v[180:181]
	v_lshlrev_b64 v[130:131], 11, v[182:183]
	v_lshl_add_u64 v[128:129], v[128:129], 0, v[152:153]
	v_lshl_add_u64 v[130:131], v[178:179], 0, v[130:131]
	v_lshlrev_b64 v[232:233], 1, v[128:129]
	global_load_dwordx4 v[132:135], v[130:131], off nt
	s_nop 0
	global_load_dwordx4 v[128:131], v[130:131], off offset:256 nt
	v_lshl_add_u64 v[234:235], s[94:95], 0, v[232:233]
	s_waitcnt vmcnt(0)
	v_lshlrev_b32_e32 v238, 16, v154
	v_and_b32_e32 v239, 0xffff0000, v154
	v_lshlrev_b32_e32 v242, 16, v156
	v_and_b32_e32 v243, 0xffff0000, v156
	v_lshlrev_b32_e32 v244, 16, v157
	v_and_b32_e32 v245, 0xffff0000, v157
	v_pk_add_f32 v[174:175], v[158:159], 1.0 op_sel_hi:[1,0]
	v_pk_add_f32 v[172:173], v[164:165], 1.0 op_sel_hi:[1,0]
	v_pk_add_f32 v[170:171], v[162:163], 1.0 op_sel_hi:[1,0]
	v_lshlrev_b32_e32 v240, 16, v155
	v_and_b32_e32 v241, 0xffff0000, v155
	v_pk_add_f32 v[176:177], v[160:161], 1.0 op_sel_hi:[1,0]
	v_pk_fma_f32 v[238:239], v[124:125], v[174:175], v[238:239]
	v_pk_fma_f32 v[244:245], v[122:123], v[172:173], v[244:245]
	v_pk_fma_f32 v[242:243], v[120:121], v[170:171], v[242:243]
	v_pk_add_f32 v[120:121], v[198:199], 1.0 op_sel_hi:[1,0]
	v_pk_add_f32 v[122:123], v[196:197], 1.0 op_sel_hi:[1,0]
	v_pk_add_f32 v[124:125], v[202:203], 1.0 op_sel_hi:[1,0]
	v_pk_add_f32 v[160:161], v[168:169], 1.0 op_sel_hi:[1,0]
	v_pk_add_f32 v[158:159], v[166:167], 1.0 op_sel_hi:[1,0]
	v_pk_add_f32 v[156:157], v[194:195], 1.0 op_sel_hi:[1,0]
	v_pk_add_f32 v[154:155], v[192:193], 1.0 op_sel_hi:[1,0]
	v_pk_fma_f32 v[240:241], v[126:127], v[176:177], v[240:241]
	v_pk_add_f32 v[126:127], v[200:201], 1.0 op_sel_hi:[1,0]
	v_pk_add_f32 v[196:197], v[206:207], 1.0 op_sel_hi:[1,0]
	v_cvt_pk_bf16_f32 v192, v238, v239
	v_cvt_pk_bf16_f32 v193, v240, v241
	v_cvt_pk_bf16_f32 v194, v242, v243
	v_cvt_pk_bf16_f32 v195, v244, v245
	v_pk_mul_f32 v[166:167], v[214:215], v[120:121]
	v_pk_mul_f32 v[168:169], v[212:213], v[122:123]
	v_pk_mul_f32 v[162:163], v[218:219], v[124:125]
	v_pk_add_f32 v[198:199], v[204:205], 1.0 op_sel_hi:[1,0]
	v_pk_mul_f32 v[164:165], v[216:217], v[126:127]
	v_pk_mul_f32 v[126:127], v[222:223], v[196:197]
	global_store_dwordx4 v[234:235], v[192:195], off
	v_pk_mul_f32 v[196:197], v[162:163], v[244:245]
	v_pk_mul_f32 v[124:125], v[220:221], v[198:199]
	v_pk_mul_f32 v[194:195], v[166:167], v[240:241]
	v_pk_mul_f32 v[192:193], v[168:169], v[238:239]
	v_pk_mul_f32 v[198:199], v[164:165], v[242:243]
	v_cvt_pk_bf16_f32 v192, v192, v193
	v_cvt_pk_bf16_f32 v193, v194, v195
	v_mul_f32_e32 v191, v239, v239
	v_cvt_pk_bf16_f32 v194, v198, v199
	v_cvt_pk_bf16_f32 v195, v196, v197
	v_lshl_add_u64 v[196:197], s[10:11], 0, v[232:233]
	global_store_dwordx4 v[196:197], v[192:195], off
	v_fmac_f32_e32 v191, v238, v238
	v_pk_add_f32 v[200:201], v[210:211], 1.0 op_sel_hi:[1,0]
	v_mul_f32_e32 v192, v241, v241
	v_fmac_f32_e32 v192, v240, v240
	v_add_f32_e32 v191, v191, v192
	v_mul_f32_e32 v192, v243, v243
	v_mul_f32_e32 v193, v245, v245
	v_fmac_f32_e32 v192, v242, v242
	v_fmac_f32_e32 v193, v244, v244
	v_add_f32_e32 v192, v192, v193
	v_add_f32_e32 v191, v191, v192
	v_lshlrev_b32_e32 v192, 16, v228
	v_and_b32_e32 v193, 0xffff0000, v228
	v_lshlrev_b32_e32 v194, 16, v229
	v_and_b32_e32 v195, 0xffff0000, v229
	v_lshlrev_b32_e32 v198, 16, v230
	v_and_b32_e32 v199, 0xffff0000, v230
	v_pk_mul_f32 v[120:121], v[226:227], v[200:201]
	v_lshlrev_b32_e32 v200, 16, v231
	v_and_b32_e32 v201, 0xffff0000, v231
	v_pk_fma_f32 v[118:119], v[118:119], v[160:161], v[194:195]
	v_pk_fma_f32 v[116:117], v[116:117], v[158:159], v[192:193]
	v_pk_fma_f32 v[194:195], v[112:113], v[154:155], v[198:199]
	v_cvt_pk_bf16_f32 v112, v116, v117
	v_cvt_pk_bf16_f32 v113, v118, v119
	v_pk_fma_f32 v[192:193], v[114:115], v[156:157], v[200:201]
	v_cvt_pk_bf16_f32 v114, v194, v195
	v_pk_add_f32 v[202:203], v[208:209], 1.0 op_sel_hi:[1,0]
	v_cvt_pk_bf16_f32 v115, v192, v193
	global_store_dwordx4 v[234:235], v[112:115], off offset:256
	v_pk_mul_f32 v[122:123], v[224:225], v[202:203]
	v_pk_mul_f32 v[198:199], v[126:127], v[118:119]
	v_mul_f32_e32 v112, v117, v117
	v_mul_f32_e32 v113, v119, v119
	v_fmac_f32_e32 v112, v116, v116
	v_fmac_f32_e32 v113, v118, v118
	v_add_f32_e32 v112, v112, v113
	v_mul_f32_e32 v113, v195, v195
	v_mul_f32_e32 v114, v193, v193
	v_fmac_f32_e32 v113, v194, v194
	v_fmac_f32_e32 v114, v192, v192
	v_add_f32_e32 v113, v113, v114
	v_add_f32_e32 v112, v112, v113
	v_and_b32_e32 v114, 64, v190
	v_add_f32_e32 v113, v191, v112
	v_xor_b32_e32 v112, 16, v190
	v_add_u32_e32 v191, 64, v114
	v_cmp_lt_i32_e32 vcc, v112, v191
	v_pk_mul_f32 v[114:115], v[124:125], v[116:117]
	v_pk_mul_f32 v[118:119], v[122:123], v[194:195]
	v_cndmask_b32_e32 v112, v190, v112, vcc
	v_lshlrev_b32_e32 v112, 2, v112
	ds_bpermute_b32 v200, v112, v113
	v_cvt_pk_bf16_f32 v116, v114, v115
	v_pk_mul_f32 v[192:193], v[120:121], v[192:193]
	v_cvt_pk_bf16_f32 v117, v198, v199
	v_cvt_pk_bf16_f32 v118, v118, v119
	s_waitcnt lgkmcnt(0)
	v_add_f32_e32 v114, v113, v200
	v_xor_b32_e32 v113, 32, v190
	v_cmp_lt_i32_e32 vcc, v113, v191
	v_cvt_pk_bf16_f32 v119, v192, v193
	global_store_dwordx4 v[196:197], v[116:119], off offset:256
	s_nop 0
	v_cndmask_b32_e32 v113, v190, v113, vcc
	v_lshlrev_b32_e32 v113, 2, v113
	ds_bpermute_b32 v115, v113, v114
	s_and_saveexec_b64 s[28:29], s[0:1]
	s_cbranch_execz .LBB0_1031
	v_lshl_add_u64 v[116:117], v[180:181], 2, s[14:15]
	s_waitcnt lgkmcnt(0)
	v_add_f32_e32 v114, v114, v115
	global_atomic_add_f32 v[116:117], v114, off

.LBB0_1033:
	s_or_b64 exec, exec, s[28:29]
	v_or_b32_e32 v106, 32, v180
	v_ashrrev_i32_e32 v107, 31, v106
	s_waitcnt lgkmcnt(0)
	v_lshlrev_b64 v[96:97], 11, v[106:107]
	v_lshl_add_u64 v[96:97], v[178:179], 0, v[96:97]
	global_load_dwordx4 v[108:111], v[96:97], off nt
	global_load_dwordx4 v[114:117], v[96:97], off offset:256 nt
	v_or_b32_e32 v104, 48, v180
	v_ashrrev_i32_e32 v105, 31, v104
	v_lshlrev_b64 v[96:97], 11, v[104:105]
	v_lshlrev_b64 v[98:99], 10, v[106:107]
	v_lshl_add_u64 v[96:97], v[178:179], 0, v[96:97]
	v_lshl_add_u64 v[118:119], v[98:99], 0, v[152:153]
	global_load_dwordx4 v[100:103], v[96:97], off nt
	s_nop 0
	global_load_dwordx4 v[96:99], v[96:97], off offset:256 nt
	v_lshlrev_b64 v[118:119], 1, v[118:119]
	v_lshl_add_u64 v[128:129], s[94:95], 0, v[118:119]
	v_lshl_add_u64 v[118:119], s[10:11], 0, v[118:119]
	s_waitcnt vmcnt(3)
	v_lshlrev_b32_e32 v130, 16, v108
	v_and_b32_e32 v131, 0xffff0000, v108
	v_lshlrev_b32_e32 v108, 16, v109
	v_and_b32_e32 v109, 0xffff0000, v109
	v_lshlrev_b32_e32 v132, 16, v110
	v_and_b32_e32 v133, 0xffff0000, v110
	v_lshlrev_b32_e32 v110, 16, v111
	v_and_b32_e32 v111, 0xffff0000, v111
	s_waitcnt vmcnt(2)
	v_lshlrev_b32_e32 v134, 16, v114
	v_and_b32_e32 v135, 0xffff0000, v114
	v_lshlrev_b32_e32 v114, 16, v115
	v_and_b32_e32 v115, 0xffff0000, v115
	v_lshlrev_b32_e32 v182, 16, v116
	v_and_b32_e32 v183, 0xffff0000, v116
	v_lshlrev_b32_e32 v116, 16, v117
	v_and_b32_e32 v117, 0xffff0000, v117
	v_pk_fma_f32 v[94:95], v[94:95], v[176:177], v[108:109]
	v_pk_fma_f32 v[92:93], v[92:93], v[174:175], v[130:131]
	v_pk_fma_f32 v[90:91], v[90:91], v[172:173], v[110:111]
	v_pk_fma_f32 v[88:89], v[88:89], v[170:171], v[132:133]
	v_pk_fma_f32 v[86:87], v[86:87], v[160:161], v[114:115]
	v_pk_fma_f32 v[84:85], v[84:85], v[158:159], v[134:135]
	v_pk_fma_f32 v[108:109], v[82:83], v[156:157], v[116:117]
	v_pk_fma_f32 v[110:111], v[80:81], v[154:155], v[182:183]
	v_cvt_pk_bf16_f32 v80, v92, v93
	v_cvt_pk_bf16_f32 v81, v94, v95
	v_cvt_pk_bf16_f32 v82, v88, v89
	v_cvt_pk_bf16_f32 v83, v90, v91
	v_pk_mul_f32 v[114:115], v[166:167], v[94:95]
	v_pk_mul_f32 v[116:117], v[168:169], v[92:93]
	v_pk_mul_f32 v[130:131], v[162:163], v[90:91]
	v_pk_mul_f32 v[132:133], v[164:165], v[88:89]
	v_mul_f32_e32 v93, v93, v93
	v_mul_f32_e32 v95, v95, v95
	v_mul_f32_e32 v89, v89, v89
	v_mul_f32_e32 v91, v91, v91
	v_mul_f32_e32 v181, v85, v85
	v_mul_f32_e32 v182, v87, v87
	v_mul_f32_e32 v183, v111, v111
	v_mul_f32_e32 v191, v109, v109
	global_store_dwordx4 v[128:129], v[80:83], off
	v_fmac_f32_e32 v93, v92, v92
	v_fmac_f32_e32 v95, v94, v94
	v_cvt_pk_bf16_f32 v80, v116, v117
	v_cvt_pk_bf16_f32 v81, v114, v115
	v_fmac_f32_e32 v89, v88, v88
	v_fmac_f32_e32 v91, v90, v90
	v_fmac_f32_e32 v181, v84, v84
	v_fmac_f32_e32 v182, v86, v86
	v_fmac_f32_e32 v183, v110, v110
	v_fmac_f32_e32 v191, v108, v108
	v_pk_mul_f32 v[134:135], v[126:127], v[86:87]
	v_cvt_pk_bf16_f32 v82, v132, v133
	v_cvt_pk_bf16_f32 v83, v130, v131
	global_store_dwordx4 v[118:119], v[80:83], off
	v_add_f32_e32 v88, v93, v95
	v_add_f32_e32 v89, v89, v91
	v_cvt_pk_bf16_f32 v80, v84, v85
	v_cvt_pk_bf16_f32 v81, v86, v87
	v_add_f32_e32 v86, v181, v182
	v_add_f32_e32 v87, v183, v191
	v_cvt_pk_bf16_f32 v82, v110, v111
	v_cvt_pk_bf16_f32 v83, v108, v109
	v_add_f32_e32 v88, v88, v89
	global_store_dwordx4 v[128:129], v[80:83], off offset:256
	s_nop 1
	v_add_f32_e32 v80, v86, v87
	v_add_f32_e32 v83, v88, v80
	ds_bpermute_b32 v88, v112, v83
	v_pk_mul_f32 v[80:81], v[124:125], v[84:85]
	v_pk_mul_f32 v[84:85], v[122:123], v[110:111]
	v_cvt_pk_bf16_f32 v82, v80, v81
	v_pk_mul_f32 v[86:87], v[120:121], v[108:109]
	s_waitcnt lgkmcnt(0)
	v_add_f32_e32 v80, v83, v88
	ds_bpermute_b32 v81, v113, v80
	v_cvt_pk_bf16_f32 v83, v134, v135
	v_cvt_pk_bf16_f32 v84, v84, v85
	v_cvt_pk_bf16_f32 v85, v86, v87
	global_store_dwordx4 v[118:119], v[82:85], off offset:256
	s_and_saveexec_b64 s[28:29], s[0:1]
	s_cbranch_execz .LBB0_1035
	v_lshl_add_u64 v[82:83], v[106:107], 2, s[14:15]
	s_waitcnt lgkmcnt(0)
	v_add_f32_e32 v80, v80, v81
	global_atomic_add_f32 v[82:83], v80, off

.LBB0_1037:
	s_or_b64 exec, exec, s[28:29]
	v_add_u32_e32 v74, 0x80, v180
	v_ashrrev_i32_e32 v75, 31, v74
	s_waitcnt lgkmcnt(0)
	v_lshlrev_b64 v[64:65], 11, v[74:75]
	v_lshl_add_u64 v[64:65], v[178:179], 0, v[64:65]
	global_load_dwordx4 v[76:79], v[64:65], off nt
	global_load_dwordx4 v[80:83], v[64:65], off offset:256 nt
	v_add_u32_e32 v72, 0x90, v180
	v_ashrrev_i32_e32 v73, 31, v72
	v_lshlrev_b64 v[64:65], 11, v[72:73]
	v_lshlrev_b64 v[66:67], 10, v[74:75]
	v_lshl_add_u64 v[64:65], v[178:179], 0, v[64:65]
	v_lshl_add_u64 v[84:85], v[66:67], 0, v[152:153]
	global_load_dwordx4 v[68:71], v[64:65], off nt
	s_nop 0
	global_load_dwordx4 v[64:67], v[64:65], off offset:256 nt
	v_lshlrev_b64 v[84:85], 1, v[84:85]
	v_lshl_add_u64 v[86:87], s[94:95], 0, v[84:85]
	v_lshl_add_u64 v[84:85], s[10:11], 0, v[84:85]
	s_waitcnt vmcnt(3)
	v_lshlrev_b32_e32 v88, 16, v76
	v_and_b32_e32 v89, 0xffff0000, v76
	v_lshlrev_b32_e32 v76, 16, v77
	v_and_b32_e32 v77, 0xffff0000, v77
	v_lshlrev_b32_e32 v90, 16, v78
	v_and_b32_e32 v91, 0xffff0000, v78
	v_lshlrev_b32_e32 v78, 16, v79
	v_and_b32_e32 v79, 0xffff0000, v79
	s_waitcnt vmcnt(2)
	v_lshlrev_b32_e32 v92, 16, v80
	v_and_b32_e32 v93, 0xffff0000, v80
	v_lshlrev_b32_e32 v80, 16, v81
	v_and_b32_e32 v81, 0xffff0000, v81
	v_lshlrev_b32_e32 v94, 16, v82
	v_and_b32_e32 v95, 0xffff0000, v82
	v_lshlrev_b32_e32 v82, 16, v83
	v_and_b32_e32 v83, 0xffff0000, v83
	v_pk_fma_f32 v[62:63], v[62:63], v[176:177], v[76:77]
	v_pk_fma_f32 v[60:61], v[60:61], v[174:175], v[88:89]
	v_pk_fma_f32 v[58:59], v[58:59], v[172:173], v[78:79]
	v_pk_fma_f32 v[56:57], v[56:57], v[170:171], v[90:91]
	v_pk_fma_f32 v[54:55], v[54:55], v[160:161], v[80:81]
	v_pk_fma_f32 v[52:53], v[52:53], v[158:159], v[92:93]
	v_pk_fma_f32 v[76:77], v[50:51], v[156:157], v[82:83]
	v_pk_fma_f32 v[78:79], v[48:49], v[154:155], v[94:95]
	v_cvt_pk_bf16_f32 v48, v60, v61
	v_cvt_pk_bf16_f32 v49, v62, v63
	v_cvt_pk_bf16_f32 v50, v56, v57
	v_cvt_pk_bf16_f32 v51, v58, v59
	v_pk_mul_f32 v[80:81], v[166:167], v[62:63]
	v_pk_mul_f32 v[82:83], v[168:169], v[60:61]
	v_pk_mul_f32 v[88:89], v[162:163], v[58:59]
	v_pk_mul_f32 v[90:91], v[164:165], v[56:57]
	v_mul_f32_e32 v61, v61, v61
	v_mul_f32_e32 v63, v63, v63
	v_mul_f32_e32 v57, v57, v57
	v_mul_f32_e32 v59, v59, v59
	v_mul_f32_e32 v94, v53, v53
	v_mul_f32_e32 v95, v55, v55
	v_mul_f32_e32 v96, v79, v79
	v_mul_f32_e32 v97, v77, v77
	global_store_dwordx4 v[86:87], v[48:51], off
	v_fmac_f32_e32 v61, v60, v60
	v_fmac_f32_e32 v63, v62, v62
	v_cvt_pk_bf16_f32 v48, v82, v83
	v_cvt_pk_bf16_f32 v49, v80, v81
	v_fmac_f32_e32 v57, v56, v56
	v_fmac_f32_e32 v59, v58, v58
	v_fmac_f32_e32 v94, v52, v52
	v_fmac_f32_e32 v95, v54, v54
	v_fmac_f32_e32 v96, v78, v78
	v_fmac_f32_e32 v97, v76, v76
	v_pk_mul_f32 v[92:93], v[126:127], v[54:55]
	v_cvt_pk_bf16_f32 v50, v90, v91
	v_cvt_pk_bf16_f32 v51, v88, v89
	global_store_dwordx4 v[84:85], v[48:51], off
	v_add_f32_e32 v56, v61, v63
	v_add_f32_e32 v57, v57, v59
	v_cvt_pk_bf16_f32 v48, v52, v53
	v_cvt_pk_bf16_f32 v49, v54, v55
	v_add_f32_e32 v54, v94, v95
	v_add_f32_e32 v55, v96, v97
	v_cvt_pk_bf16_f32 v50, v78, v79
	v_cvt_pk_bf16_f32 v51, v76, v77
	v_add_f32_e32 v56, v56, v57
	global_store_dwordx4 v[86:87], v[48:51], off offset:256
	s_nop 1
	v_add_f32_e32 v48, v54, v55
	v_add_f32_e32 v51, v56, v48
	ds_bpermute_b32 v56, v112, v51
	v_pk_mul_f32 v[48:49], v[124:125], v[52:53]
	v_pk_mul_f32 v[52:53], v[122:123], v[78:79]
	v_cvt_pk_bf16_f32 v50, v48, v49
	v_pk_mul_f32 v[54:55], v[120:121], v[76:77]
	s_waitcnt lgkmcnt(0)
	v_add_f32_e32 v48, v51, v56
	ds_bpermute_b32 v49, v113, v48
	v_cvt_pk_bf16_f32 v51, v92, v93
	v_cvt_pk_bf16_f32 v52, v52, v53
	v_cvt_pk_bf16_f32 v53, v54, v55
	global_store_dwordx4 v[84:85], v[50:53], off offset:256
	s_and_saveexec_b64 s[28:29], s[0:1]
	s_cbranch_execz .LBB0_1039
	v_lshl_add_u64 v[50:51], v[74:75], 2, s[14:15]
	s_waitcnt lgkmcnt(0)
	v_add_f32_e32 v48, v48, v49
	global_atomic_add_f32 v[50:51], v48, off

.LBB0_1041:
	s_or_b64 exec, exec, s[28:29]
	v_add_u32_e32 v42, 0xa0, v180
	v_ashrrev_i32_e32 v43, 31, v42
	s_waitcnt lgkmcnt(0)
	v_lshlrev_b64 v[32:33], 11, v[42:43]
	v_lshl_add_u64 v[32:33], v[178:179], 0, v[32:33]
	global_load_dwordx4 v[44:47], v[32:33], off nt
	global_load_dwordx4 v[48:51], v[32:33], off offset:256 nt
	v_add_u32_e32 v40, 0xb0, v180
	v_ashrrev_i32_e32 v41, 31, v40
	v_lshlrev_b64 v[32:33], 11, v[40:41]
	v_lshlrev_b64 v[34:35], 10, v[42:43]
	v_lshl_add_u64 v[32:33], v[178:179], 0, v[32:33]
	v_lshl_add_u64 v[52:53], v[34:35], 0, v[152:153]
	global_load_dwordx4 v[36:39], v[32:33], off nt
	s_nop 0
	global_load_dwordx4 v[32:35], v[32:33], off offset:256 nt
	v_lshlrev_b64 v[52:53], 1, v[52:53]
	v_lshl_add_u64 v[54:55], s[94:95], 0, v[52:53]
	v_lshl_add_u64 v[52:53], s[10:11], 0, v[52:53]
	s_waitcnt vmcnt(3)
	v_lshlrev_b32_e32 v56, 16, v44
	v_and_b32_e32 v57, 0xffff0000, v44
	v_lshlrev_b32_e32 v44, 16, v45
	v_and_b32_e32 v45, 0xffff0000, v45
	v_lshlrev_b32_e32 v58, 16, v46
	v_and_b32_e32 v59, 0xffff0000, v46
	v_lshlrev_b32_e32 v46, 16, v47
	v_and_b32_e32 v47, 0xffff0000, v47
	s_waitcnt vmcnt(2)
	v_lshlrev_b32_e32 v60, 16, v48
	v_and_b32_e32 v61, 0xffff0000, v48
	v_lshlrev_b32_e32 v48, 16, v49
	v_and_b32_e32 v49, 0xffff0000, v49
	v_lshlrev_b32_e32 v62, 16, v50
	v_and_b32_e32 v63, 0xffff0000, v50
	v_lshlrev_b32_e32 v50, 16, v51
	v_and_b32_e32 v51, 0xffff0000, v51
	v_pk_fma_f32 v[30:31], v[30:31], v[176:177], v[44:45]
	v_pk_fma_f32 v[28:29], v[28:29], v[174:175], v[56:57]
	v_pk_fma_f32 v[26:27], v[26:27], v[172:173], v[46:47]
	v_pk_fma_f32 v[24:25], v[24:25], v[170:171], v[58:59]
	v_pk_fma_f32 v[22:23], v[22:23], v[160:161], v[48:49]
	v_pk_fma_f32 v[20:21], v[20:21], v[158:159], v[60:61]
	v_pk_fma_f32 v[44:45], v[18:19], v[156:157], v[50:51]
	v_pk_fma_f32 v[46:47], v[16:17], v[154:155], v[62:63]
	v_cvt_pk_bf16_f32 v16, v28, v29
	v_cvt_pk_bf16_f32 v17, v30, v31
	v_cvt_pk_bf16_f32 v18, v24, v25
	v_cvt_pk_bf16_f32 v19, v26, v27
	v_pk_mul_f32 v[48:49], v[166:167], v[30:31]
	v_pk_mul_f32 v[50:51], v[168:169], v[28:29]
	v_pk_mul_f32 v[56:57], v[162:163], v[26:27]
	v_pk_mul_f32 v[58:59], v[164:165], v[24:25]
	v_mul_f32_e32 v29, v29, v29
	v_mul_f32_e32 v31, v31, v31
	v_mul_f32_e32 v25, v25, v25
	v_mul_f32_e32 v27, v27, v27
	v_mul_f32_e32 v62, v21, v21
	v_mul_f32_e32 v63, v23, v23
	v_mul_f32_e32 v64, v47, v47
	v_mul_f32_e32 v65, v45, v45
	global_store_dwordx4 v[54:55], v[16:19], off
	v_fmac_f32_e32 v29, v28, v28
	v_fmac_f32_e32 v31, v30, v30
	v_cvt_pk_bf16_f32 v16, v50, v51
	v_cvt_pk_bf16_f32 v17, v48, v49
	v_fmac_f32_e32 v25, v24, v24
	v_fmac_f32_e32 v27, v26, v26
	v_fmac_f32_e32 v62, v20, v20
	v_fmac_f32_e32 v63, v22, v22
	v_fmac_f32_e32 v64, v46, v46
	v_fmac_f32_e32 v65, v44, v44
	v_pk_mul_f32 v[60:61], v[126:127], v[22:23]
	v_cvt_pk_bf16_f32 v18, v58, v59
	v_cvt_pk_bf16_f32 v19, v56, v57
	global_store_dwordx4 v[52:53], v[16:19], off
	v_add_f32_e32 v24, v29, v31
	v_add_f32_e32 v25, v25, v27
	v_cvt_pk_bf16_f32 v16, v20, v21
	v_cvt_pk_bf16_f32 v17, v22, v23
	v_add_f32_e32 v22, v62, v63
	v_add_f32_e32 v23, v64, v65
	v_cvt_pk_bf16_f32 v18, v46, v47
	v_cvt_pk_bf16_f32 v19, v44, v45
	v_add_f32_e32 v24, v24, v25
	global_store_dwordx4 v[54:55], v[16:19], off offset:256
	s_nop 1
	v_add_f32_e32 v16, v22, v23
	v_add_f32_e32 v19, v24, v16
	ds_bpermute_b32 v24, v112, v19
	v_pk_mul_f32 v[16:17], v[124:125], v[20:21]
	v_pk_mul_f32 v[20:21], v[122:123], v[46:47]
	v_cvt_pk_bf16_f32 v18, v16, v17
	v_pk_mul_f32 v[22:23], v[120:121], v[44:45]
	s_waitcnt lgkmcnt(0)
	v_add_f32_e32 v16, v19, v24
	ds_bpermute_b32 v17, v113, v16
	v_cvt_pk_bf16_f32 v19, v60, v61
	v_cvt_pk_bf16_f32 v20, v20, v21
	v_cvt_pk_bf16_f32 v21, v22, v23
	global_store_dwordx4 v[52:53], v[18:21], off offset:256
	s_and_saveexec_b64 s[28:29], s[0:1]
	s_cbranch_execz .LBB0_1043
	v_lshl_add_u64 v[18:19], v[42:43], 2, s[14:15]
	s_waitcnt lgkmcnt(0)
	v_add_f32_e32 v16, v16, v17
	global_atomic_add_f32 v[18:19], v16, off

.LBB0_1199:
	s_ashr_i32 s14, s39, 4
	v_lshl_or_b32 v144, s40, 8, v170
	v_lshl_add_u32 v164, s39, 8, v168
	s_mul_hi_i32 s15, s14, 0x9000
	s_mul_i32 s14, s14, 0x9000
	v_ashrrev_i32_e32 v145, 31, v144
	v_ashrrev_i32_e32 v165, 31, v164
	s_add_u32 s14, s29, s14
	v_lshl_add_u64 v[162:163], v[144:145], 1, s[94:95]
	v_lshlrev_b64 v[146:147], 11, v[164:165]
	v_lshlrev_b64 v[144:145], 2, v[144:145]
	s_addc_u32 s15, s30, s15
	v_lshl_add_u64 v[150:151], v[162:163], 0, v[146:147]
	v_lshl_add_u64 v[166:167], s[14:15], 0, v[144:145]
	global_load_dwordx4 v[146:149], v[150:151], off nt
	s_nop 0
	global_load_dwordx4 v[150:153], v[150:151], off offset:256 nt
	s_nop 0
	global_load_dwordx4 v[154:157], v[166:167], off
	global_load_dwordx4 v[158:161], v[166:167], off offset:16
	v_or_b32_e32 v206, 16, v164
	global_load_dwordx4 v[174:177], v[166:167], off offset:528
	global_load_dwordx4 v[178:181], v[166:167], off offset:512
	v_ashrrev_i32_e32 v207, 31, v206
	v_lshlrev_b64 v[166:167], 11, v[206:207]
	v_or_b32_e32 v208, 32, v164
	v_lshl_add_u64 v[166:167], v[162:163], 0, v[166:167]
	v_ashrrev_i32_e32 v209, 31, v208
	global_load_dwordx4 v[182:185], v[166:167], off nt
	global_load_dwordx4 v[186:189], v[166:167], off offset:256 nt
	v_lshlrev_b64 v[166:167], 11, v[208:209]
	v_lshl_add_u64 v[166:167], v[162:163], 0, v[166:167]
	global_load_dwordx4 v[190:193], v[166:167], off nt
	global_load_dwordx4 v[194:197], v[166:167], off offset:256 nt
	v_or_b32_e32 v166, 48, v164
	v_ashrrev_i32_e32 v167, 31, v166
	v_lshlrev_b64 v[198:199], 11, v[166:167]
	v_lshl_add_u64 v[202:203], v[162:163], 0, v[198:199]
	global_load_dwordx4 v[198:201], v[202:203], off nt
	s_nop 0
	global_load_dwordx4 v[202:205], v[202:203], off offset:256 nt
	s_and_b64 vcc, exec, s[0:1]
	s_mov_b64 s[0:1], -1
	s_waitcnt vmcnt(0)
	v_lshlrev_b32_e32 v214, 16, v148
	v_and_b32_e32 v215, 0xffff0000, v148
	v_lshlrev_b32_e32 v216, 16, v149
	v_and_b32_e32 v217, 0xffff0000, v149
	v_pk_add_f32 v[148:149], v[154:155], 1.0 op_sel_hi:[1,0]
	v_lshlrev_b32_e32 v210, 16, v146
	v_and_b32_e32 v211, 0xffff0000, v146
	v_lshlrev_b32_e32 v222, 16, v152
	v_and_b32_e32 v223, 0xffff0000, v152
	v_lshlrev_b32_e32 v224, 16, v153
	v_and_b32_e32 v225, 0xffff0000, v153
	v_pk_add_f32 v[152:153], v[158:159], 1.0 op_sel_hi:[1,0]
	v_pk_mul_f32 v[158:159], v[148:149], 0.5 op_sel_hi:[1,0]
	v_lshlrev_b32_e32 v212, 16, v147
	v_and_b32_e32 v213, 0xffff0000, v147
	v_lshlrev_b32_e32 v218, 16, v150
	v_and_b32_e32 v219, 0xffff0000, v150
	v_lshlrev_b32_e32 v220, 16, v151
	v_and_b32_e32 v221, 0xffff0000, v151
	v_pk_add_f32 v[146:147], v[156:157], 1.0 op_sel_hi:[1,0]
	v_pk_add_f32 v[150:151], v[160:161], 1.0 op_sel_hi:[1,0]
	v_pk_add_f32 v[180:181], v[180:181], 1.0 op_sel_hi:[1,0]
	v_pk_add_f32 v[178:179], v[178:179], 1.0 op_sel_hi:[1,0]
	v_pk_add_f32 v[174:175], v[174:175], 1.0 op_sel_hi:[1,0]
	v_pk_fma_f32 v[124:125], v[124:125], v[158:159], v[210:211]
	v_lshlrev_b64 v[210:211], 12, v[164:165]
	v_pk_add_f32 v[176:177], v[176:177], 1.0 op_sel_hi:[1,0]
	v_pk_mul_f32 v[160:161], v[146:147], 0.5 op_sel_hi:[1,0]
	v_pk_mul_f32 v[156:157], v[150:151], 0.5 op_sel_hi:[1,0]
	v_pk_mul_f32 v[154:155], v[152:153], 0.5 op_sel_hi:[1,0]
	v_pk_mul_f32 v[152:153], v[180:181], 0.5 op_sel_hi:[1,0]
	v_pk_mul_f32 v[150:151], v[178:179], 0.5 op_sel_hi:[1,0]
	v_pk_mul_f32 v[146:147], v[174:175], 0.5 op_sel_hi:[1,0]
	v_lshl_add_u64 v[210:211], s[80:81], 0, v[210:211]
	v_lshlrev_b32_e32 v226, 16, v182
	v_and_b32_e32 v227, 0xffff0000, v182
	v_pk_mul_f32 v[148:149], v[176:177], 0.5 op_sel_hi:[1,0]
	v_pk_fma_f32 v[126:127], v[126:127], v[160:161], v[212:213]
	v_lshl_add_u64 v[210:211], v[210:211], 0, v[144:145]
	v_pk_fma_f32 v[116:117], v[116:117], v[150:151], v[218:219]
	v_pk_fma_f32 v[118:119], v[118:119], v[152:153], v[220:221]
	v_pk_fma_f32 v[108:109], v[108:109], v[146:147], v[222:223]
	v_pk_fma_f32 v[120:121], v[120:121], v[154:155], v[214:215]
	v_pk_fma_f32 v[122:123], v[122:123], v[156:157], v[216:217]
	global_store_dwordx4 v[210:211], v[124:127], off
	global_store_dwordx4 v[210:211], v[120:123], off offset:16
	v_pk_fma_f32 v[110:111], v[110:111], v[148:149], v[224:225]
	global_store_dwordx4 v[210:211], v[116:119], off offset:512
	global_store_dwordx4 v[210:211], v[108:111], off offset:528
	v_lshlrev_b32_e32 v182, 16, v183
	v_and_b32_e32 v183, 0xffff0000, v183
	v_pk_fma_f32 v[108:109], v[112:113], v[158:159], v[226:227]
	v_lshlrev_b64 v[112:113], 12, v[206:207]
	v_lshlrev_b32_e32 v230, 16, v186
	v_and_b32_e32 v231, 0xffff0000, v186
	v_lshlrev_b32_e32 v186, 16, v187
	v_and_b32_e32 v187, 0xffff0000, v187
	v_lshlrev_b32_e32 v232, 16, v188
	v_and_b32_e32 v233, 0xffff0000, v188
	v_lshl_add_u64 v[112:113], s[80:81], 0, v[112:113]
	v_lshlrev_b32_e32 v228, 16, v184
	v_and_b32_e32 v229, 0xffff0000, v184
	v_lshlrev_b32_e32 v184, 16, v185
	v_and_b32_e32 v185, 0xffff0000, v185
	v_lshlrev_b32_e32 v188, 16, v189
	v_and_b32_e32 v189, 0xffff0000, v189
	v_lshlrev_b32_e32 v234, 16, v190
	v_and_b32_e32 v235, 0xffff0000, v190
	v_pk_fma_f32 v[110:111], v[114:115], v[160:161], v[182:183]
	v_lshl_add_u64 v[112:113], v[112:113], 0, v[144:145]
	v_pk_fma_f32 v[102:103], v[102:103], v[152:153], v[186:187]
	v_pk_fma_f32 v[100:101], v[100:101], v[150:151], v[230:231]
	v_pk_fma_f32 v[92:93], v[92:93], v[146:147], v[232:233]
	v_pk_fma_f32 v[106:107], v[106:107], v[156:157], v[184:185]
	v_pk_fma_f32 v[104:105], v[104:105], v[154:155], v[228:229]
	global_store_dwordx4 v[112:113], v[108:111], off
	global_store_dwordx4 v[112:113], v[104:107], off offset:16
	v_pk_fma_f32 v[94:95], v[94:95], v[148:149], v[188:189]
	global_store_dwordx4 v[112:113], v[100:103], off offset:512
	global_store_dwordx4 v[112:113], v[92:95], off offset:528
	v_lshlrev_b32_e32 v174, 16, v191
	v_and_b32_e32 v175, 0xffff0000, v191
	v_pk_fma_f32 v[92:93], v[96:97], v[158:159], v[234:235]
	v_lshlrev_b64 v[96:97], 12, v[208:209]
	v_lshlrev_b32_e32 v176, 16, v192
	v_and_b32_e32 v177, 0xffff0000, v192
	v_lshlrev_b32_e32 v178, 16, v193
	v_and_b32_e32 v179, 0xffff0000, v193
	v_lshlrev_b32_e32 v180, 16, v194
	v_and_b32_e32 v181, 0xffff0000, v194
	v_lshlrev_b32_e32 v190, 16, v195
	v_and_b32_e32 v191, 0xffff0000, v195
	v_lshlrev_b32_e32 v192, 16, v196
	v_and_b32_e32 v193, 0xffff0000, v196
	v_lshl_add_u64 v[96:97], s[80:81], 0, v[96:97]
	v_lshlrev_b32_e32 v194, 16, v197
	v_and_b32_e32 v195, 0xffff0000, v197
	v_lshlrev_b32_e32 v196, 16, v198
	v_and_b32_e32 v197, 0xffff0000, v198
	v_pk_fma_f32 v[94:95], v[98:99], v[160:161], v[174:175]
	v_lshl_add_u64 v[96:97], v[96:97], 0, v[144:145]
	v_pk_fma_f32 v[86:87], v[86:87], v[152:153], v[190:191]
	v_pk_fma_f32 v[84:85], v[84:85], v[150:151], v[180:181]
	v_pk_fma_f32 v[76:77], v[76:77], v[146:147], v[192:193]
	v_pk_fma_f32 v[90:91], v[90:91], v[156:157], v[178:179]
	v_pk_fma_f32 v[88:89], v[88:89], v[154:155], v[176:177]
	global_store_dwordx4 v[96:97], v[92:95], off
	global_store_dwordx4 v[96:97], v[88:91], off offset:16
	v_pk_fma_f32 v[78:79], v[78:79], v[148:149], v[194:195]
	global_store_dwordx4 v[96:97], v[84:87], off offset:512
	global_store_dwordx4 v[96:97], v[76:79], off offset:528
	v_lshlrev_b32_e32 v198, 16, v199
	v_and_b32_e32 v199, 0xffff0000, v199
	v_pk_fma_f32 v[76:77], v[80:81], v[158:159], v[196:197]
	v_lshlrev_b64 v[80:81], 12, v[166:167]
	v_lshlrev_b32_e32 v238, 16, v202
	v_and_b32_e32 v239, 0xffff0000, v202
	v_lshlrev_b32_e32 v202, 16, v203
	v_and_b32_e32 v203, 0xffff0000, v203
	v_lshlrev_b32_e32 v240, 16, v204
	v_and_b32_e32 v241, 0xffff0000, v204
	v_lshl_add_u64 v[80:81], s[80:81], 0, v[80:81]
	v_add_u32_e32 v98, 0x80, v164
	v_lshlrev_b32_e32 v236, 16, v200
	v_and_b32_e32 v237, 0xffff0000, v200
	v_lshlrev_b32_e32 v200, 16, v201
	v_and_b32_e32 v201, 0xffff0000, v201
	v_lshlrev_b32_e32 v204, 16, v205
	v_and_b32_e32 v205, 0xffff0000, v205
	v_pk_fma_f32 v[78:79], v[82:83], v[160:161], v[198:199]
	v_lshl_add_u64 v[80:81], v[80:81], 0, v[144:145]
	v_pk_fma_f32 v[70:71], v[70:71], v[152:153], v[202:203]
	v_pk_fma_f32 v[68:69], v[68:69], v[150:151], v[238:239]
	v_pk_fma_f32 v[64:65], v[64:65], v[146:147], v[240:241]
	v_ashrrev_i32_e32 v99, 31, v98
	v_pk_fma_f32 v[74:75], v[74:75], v[156:157], v[200:201]
	v_pk_fma_f32 v[72:73], v[72:73], v[154:155], v[236:237]
	global_store_dwordx4 v[80:81], v[76:79], off
	global_store_dwordx4 v[80:81], v[72:75], off offset:16
	v_pk_fma_f32 v[66:67], v[66:67], v[148:149], v[204:205]
	global_store_dwordx4 v[80:81], v[68:71], off offset:512
	global_store_dwordx4 v[80:81], v[64:67], off offset:528
	v_add_u32_e32 v100, 0x90, v164
	v_ashrrev_i32_e32 v101, 31, v100
	v_lshlrev_b64 v[64:65], 11, v[98:99]
	v_lshl_add_u64 v[64:65], v[162:163], 0, v[64:65]
	global_load_dwordx4 v[66:69], v[64:65], off nt
	global_load_dwordx4 v[70:73], v[64:65], off offset:256 nt
	v_lshlrev_b64 v[64:65], 11, v[100:101]
	v_add_u32_e32 v102, 0xa0, v164
	v_lshl_add_u64 v[64:65], v[162:163], 0, v[64:65]
	v_ashrrev_i32_e32 v103, 31, v102
	global_load_dwordx4 v[74:77], v[64:65], off nt
	global_load_dwordx4 v[78:81], v[64:65], off offset:256 nt
	v_lshlrev_b64 v[64:65], 11, v[102:103]
	v_lshl_add_u64 v[64:65], v[162:163], 0, v[64:65]
	global_load_dwordx4 v[82:85], v[64:65], off nt
	global_load_dwordx4 v[86:89], v[64:65], off offset:256 nt
	v_add_u32_e32 v64, 0xb0, v164
	v_ashrrev_i32_e32 v65, 31, v64
	v_lshlrev_b64 v[90:91], 11, v[64:65]
	v_lshl_add_u64 v[94:95], v[162:163], 0, v[90:91]
	global_load_dwordx4 v[90:93], v[94:95], off nt
	s_nop 0
	global_load_dwordx4 v[94:97], v[94:95], off offset:256 nt
	s_waitcnt vmcnt(7)
	v_lshlrev_b32_e32 v104, 16, v66
	v_and_b32_e32 v105, 0xffff0000, v66
	v_lshlrev_b32_e32 v66, 16, v67
	v_and_b32_e32 v67, 0xffff0000, v67
	v_pk_fma_f32 v[62:63], v[62:63], v[160:161], v[66:67]
	v_lshlrev_b64 v[66:67], 12, v[98:99]
	s_waitcnt vmcnt(6)
	v_lshlrev_b32_e32 v108, 16, v70
	v_and_b32_e32 v109, 0xffff0000, v70
	v_lshlrev_b32_e32 v70, 16, v71
	v_and_b32_e32 v71, 0xffff0000, v71
	v_lshlrev_b32_e32 v110, 16, v72
	v_and_b32_e32 v111, 0xffff0000, v72
	v_lshl_add_u64 v[66:67], s[80:81], 0, v[66:67]
	v_lshlrev_b32_e32 v106, 16, v68
	v_and_b32_e32 v107, 0xffff0000, v68
	v_lshlrev_b32_e32 v68, 16, v69
	v_and_b32_e32 v69, 0xffff0000, v69
	v_lshlrev_b32_e32 v72, 16, v73
	v_and_b32_e32 v73, 0xffff0000, v73
	s_waitcnt vmcnt(5)
	v_lshlrev_b32_e32 v112, 16, v74
	v_and_b32_e32 v113, 0xffff0000, v74
	v_pk_fma_f32 v[60:61], v[60:61], v[158:159], v[104:105]
	v_lshl_add_u64 v[66:67], v[66:67], 0, v[144:145]
	v_pk_fma_f32 v[54:55], v[54:55], v[152:153], v[70:71]
	v_pk_fma_f32 v[52:53], v[52:53], v[150:151], v[108:109]
	v_pk_fma_f32 v[44:45], v[44:45], v[146:147], v[110:111]
	v_pk_fma_f32 v[58:59], v[58:59], v[156:157], v[68:69]
	v_pk_fma_f32 v[56:57], v[56:57], v[154:155], v[106:107]
	global_store_dwordx4 v[66:67], v[60:63], off
	global_store_dwordx4 v[66:67], v[56:59], off offset:16
	v_pk_fma_f32 v[46:47], v[46:47], v[148:149], v[72:73]
	global_store_dwordx4 v[66:67], v[52:55], off offset:512
	global_store_dwordx4 v[66:67], v[44:47], off offset:528
	v_lshlrev_b32_e32 v74, 16, v75
	v_and_b32_e32 v75, 0xffff0000, v75
	v_pk_fma_f32 v[44:45], v[48:49], v[158:159], v[112:113]
	v_lshlrev_b64 v[48:49], 12, v[100:101]
	s_waitcnt vmcnt(8)
	v_lshlrev_b32_e32 v116, 16, v78
	v_and_b32_e32 v117, 0xffff0000, v78
	v_lshlrev_b32_e32 v78, 16, v79
	v_and_b32_e32 v79, 0xffff0000, v79
	v_lshlrev_b32_e32 v118, 16, v80
	v_and_b32_e32 v119, 0xffff0000, v80
	v_lshl_add_u64 v[48:49], s[80:81], 0, v[48:49]
	v_lshlrev_b32_e32 v114, 16, v76
	v_and_b32_e32 v115, 0xffff0000, v76
	v_lshlrev_b32_e32 v76, 16, v77
	v_and_b32_e32 v77, 0xffff0000, v77
	v_lshlrev_b32_e32 v80, 16, v81
	v_and_b32_e32 v81, 0xffff0000, v81
	s_waitcnt vmcnt(7)
	v_lshlrev_b32_e32 v120, 16, v82
	v_and_b32_e32 v121, 0xffff0000, v82
	v_pk_fma_f32 v[46:47], v[50:51], v[160:161], v[74:75]
	v_lshl_add_u64 v[48:49], v[48:49], 0, v[144:145]
	v_pk_fma_f32 v[38:39], v[38:39], v[152:153], v[78:79]
	v_pk_fma_f32 v[36:37], v[36:37], v[150:151], v[116:117]
	v_pk_fma_f32 v[28:29], v[28:29], v[146:147], v[118:119]
	v_pk_fma_f32 v[42:43], v[42:43], v[156:157], v[76:77]
	v_pk_fma_f32 v[40:41], v[40:41], v[154:155], v[114:115]
	global_store_dwordx4 v[48:49], v[44:47], off
	global_store_dwordx4 v[48:49], v[40:43], off offset:16
	v_pk_fma_f32 v[30:31], v[30:31], v[148:149], v[80:81]
	global_store_dwordx4 v[48:49], v[36:39], off offset:512
	global_store_dwordx4 v[48:49], v[28:31], off offset:528
	v_lshlrev_b32_e32 v82, 16, v83
	v_and_b32_e32 v83, 0xffff0000, v83
	v_pk_fma_f32 v[28:29], v[32:33], v[158:159], v[120:121]
	v_lshlrev_b64 v[32:33], 12, v[102:103]
	s_waitcnt vmcnt(10)
	v_lshlrev_b32_e32 v124, 16, v86
	v_and_b32_e32 v125, 0xffff0000, v86
	v_lshlrev_b32_e32 v86, 16, v87
	v_and_b32_e32 v87, 0xffff0000, v87
	v_lshlrev_b32_e32 v126, 16, v88
	v_and_b32_e32 v127, 0xffff0000, v88
	v_lshl_add_u64 v[32:33], s[80:81], 0, v[32:33]
	v_lshlrev_b32_e32 v122, 16, v84
	v_and_b32_e32 v123, 0xffff0000, v84
	v_lshlrev_b32_e32 v84, 16, v85
	v_and_b32_e32 v85, 0xffff0000, v85
	v_lshlrev_b32_e32 v88, 16, v89
	v_and_b32_e32 v89, 0xffff0000, v89
	s_waitcnt vmcnt(9)
	v_lshlrev_b32_e32 v162, 16, v90
	v_and_b32_e32 v163, 0xffff0000, v90
	v_pk_fma_f32 v[30:31], v[34:35], v[160:161], v[82:83]
	v_lshl_add_u64 v[32:33], v[32:33], 0, v[144:145]
	v_pk_fma_f32 v[22:23], v[22:23], v[152:153], v[86:87]
	v_pk_fma_f32 v[20:21], v[20:21], v[150:151], v[124:125]
	v_pk_fma_f32 v[12:13], v[12:13], v[146:147], v[126:127]
	v_pk_fma_f32 v[26:27], v[26:27], v[156:157], v[84:85]
	v_pk_fma_f32 v[24:25], v[24:25], v[154:155], v[122:123]
	global_store_dwordx4 v[32:33], v[28:31], off
	global_store_dwordx4 v[32:33], v[24:27], off offset:16
	v_pk_fma_f32 v[14:15], v[14:15], v[148:149], v[88:89]
	global_store_dwordx4 v[32:33], v[20:23], off offset:512
	global_store_dwordx4 v[32:33], v[12:15], off offset:528
	v_lshlrev_b32_e32 v90, 16, v91
	v_and_b32_e32 v91, 0xffff0000, v91
	v_pk_fma_f32 v[12:13], v[16:17], v[158:159], v[162:163]
	v_lshlrev_b64 v[16:17], 12, v[64:65]
	s_waitcnt vmcnt(12)
	v_lshlrev_b32_e32 v166, 16, v94
	v_and_b32_e32 v167, 0xffff0000, v94
	v_lshlrev_b32_e32 v94, 16, v95
	v_and_b32_e32 v95, 0xffff0000, v95
	v_lshl_add_u64 v[16:17], s[80:81], 0, v[16:17]
	v_lshlrev_b32_e32 v164, 16, v92
	v_and_b32_e32 v165, 0xffff0000, v92
	v_lshlrev_b32_e32 v92, 16, v93
	v_and_b32_e32 v93, 0xffff0000, v93
	v_lshlrev_b32_e32 v174, 16, v96
	v_and_b32_e32 v175, 0xffff0000, v96
	v_lshlrev_b32_e32 v96, 16, v97
	v_and_b32_e32 v97, 0xffff0000, v97
	v_pk_fma_f32 v[14:15], v[18:19], v[160:161], v[90:91]
	v_lshl_add_u64 v[16:17], v[16:17], 0, v[144:145]
	v_pk_fma_f32 v[6:7], v[6:7], v[152:153], v[94:95]
	v_pk_fma_f32 v[4:5], v[4:5], v[150:151], v[166:167]
	v_pk_fma_f32 v[10:11], v[10:11], v[156:157], v[92:93]
	v_pk_fma_f32 v[8:9], v[8:9], v[154:155], v[164:165]
	global_store_dwordx4 v[16:17], v[12:15], off
	global_store_dwordx4 v[16:17], v[8:11], off offset:16
	v_pk_fma_f32 v[2:3], v[2:3], v[148:149], v[96:97]
	v_pk_fma_f32 v[0:1], v[0:1], v[146:147], v[174:175]
	global_store_dwordx4 v[16:17], v[4:7], off offset:512
	global_store_dwordx4 v[16:17], v[0:3], off offset:528
	s_cbranch_vccnz .LBB0_1184
	s_andn2_b64 vcc, exec, s[6:7]
	s_cbranch_vccnz .LBB0_1183
	s_barrier
	s_branch .LBB0_1183
